# diff attention tile B: row-max tree starts on the first QK block's scores (covers the last QK MFMA latency, s_nop 10 -> 3); two s_nop 0 fillers and the C-tuple guard nop removed from the common path
# speedup vs baseline: 1.0083x; 1.0022x over previous
; template <bool HAS_QK, bool HAS_PV> ...
;     ...
;     if (HAS_QK) {
;         const float c0 = beta - mrun;
; #pragma unroll
;         for (int r = 0; r < 16; ++r) { s0[r] = c0; s1[r] = c0; }
; #pragma unroll
;         for (int s4 = 0; s4 < 4; ++s4) {
;             const bf16x8 a0 = KFRAG(Kt, kb0, kb1, 0, 0, s4), a1 = KFRAG(Kt, kb0, kb1, 1, 0, s4);
;             s0 = __builtin_amdgcn_mfma_f32_32x32x16_bf16(a0, qf[s4], s0, 0, 0, 0);
;             s1 = __builtin_amdgcn_mfma_f32_32x32x16_bf16(a1, qf[s4], s1, 0, 0, 0);
;         }
.LBB0_207:
	s_waitcnt lgkmcnt(0)
	v_sub_f32_e32 v14, v0, v15
	v_cmp_neq_f32_e32 vcc, v14, v194
	s_cbranch_vccz .Lcreg_ok_a
	v_mov_b32_e32 v194, v14
	v_mov_b32_e32 v195, v14
	v_mov_b64_e32 v[196:197], v[194:195]
	v_mov_b64_e32 v[198:199], v[194:195]
	v_mov_b64_e32 v[200:201], v[194:195]
	v_mov_b64_e32 v[202:203], v[194:195]
	v_mov_b64_e32 v[204:205], v[194:195]
	v_mov_b64_e32 v[206:207], v[194:195]
	v_mov_b64_e32 v[208:209], v[194:195]
	s_nop 1
.Lcreg_ok_a:
	s_andn2_b64 vcc, exec, s[4:5]
	v_mfma_f32_32x32x16_bf16 v[128:143], v[220:223], v[144:147], v[194:209]
	ds_read_b128 v[220:223], v248 offset:512
	v_mfma_f32_32x32x16_bf16 v[80:95], v[224:227], v[144:147], v[194:209]
	ds_read_b128 v[224:227], v248 offset:8704
	v_mfma_f32_32x32x16_bf16 v[128:143], v[228:231], v[148:151], v[128:143]
	ds_read_b128 v[228:231], v249 offset:512
	v_mfma_f32_32x32x16_bf16 v[80:95], v[232:235], v[148:151], v[80:95]
	ds_read_b128 v[232:235], v249 offset:8704
	s_waitcnt lgkmcnt(3)
	v_mfma_f32_32x32x16_bf16 v[128:143], v[220:223], v[152:155], v[128:143]
	s_waitcnt lgkmcnt(2)
	v_mfma_f32_32x32x16_bf16 v[80:95], v[224:227], v[152:155], v[80:95]
	s_waitcnt lgkmcnt(1)
	v_mfma_f32_32x32x16_bf16 v[128:143], v[228:231], v[156:159], v[128:143]
	s_waitcnt lgkmcnt(0)
	v_mfma_f32_32x32x16_bf16 v[80:95], v[232:235], v[156:159], v[80:95]
	ds_read_b128 v[220:223], v248 offset:32768
	ds_read_b128 v[224:227], v249 offset:32768
	ds_read_b128 v[228:231], v248 offset:33280
	ds_read_b128 v[232:235], v249 offset:33280
	s_cmp_ge_u32 s35, s17
	s_cbranch_scc1 .Ldiff_nodma
	s_and_b32 s4, s34, 0x10000
	s_add_i32 s4, s24, s4
	v_readlane_b32 s10, v247, 0
	v_readlane_b32 s11, v247, 1
	s_add_i32 s56, s29, 0x80
	s_lshl_b32 s56, s56, 10
	s_add_u32 s10, s10, s56
	s_addc_u32 s11, s11, 0
	s_add_u32 s56, s10, s72
	s_addc_u32 s57, s11, s73
	s_mov_b32 m0, s4
	s_nop 0
	global_load_lds_dwordx4 v250, s[56:57]
	s_add_i32 m0, s4, 0x2000
	s_nop 0
	global_load_lds_dwordx4 v251, s[56:57]
	s_add_u32 s56, s10, s74
	s_addc_u32 s57, s11, s75
	s_add_i32 m0, s4, 0x4000
	s_nop 0
	global_load_lds_dwordx4 v250, s[56:57]
	s_add_i32 m0, s4, 0x6000
	s_nop 0
	global_load_lds_dwordx4 v251, s[56:57]
	s_add_u32 s56, s10, s68
	s_addc_u32 s57, s11, s69
	s_add_i32 m0, s4, 0x8000
	s_nop 0
	global_load_lds_dwordx4 v250, s[56:57]
	s_add_i32 m0, s4, 0xa000
	s_nop 0
	global_load_lds_dwordx4 v251, s[56:57]
	s_add_u32 s56, s10, s96
	s_addc_u32 s57, s11, s97
	s_add_i32 m0, s4, 0xc000
	s_nop 0
	global_load_lds_dwordx4 v250, s[56:57]
	s_add_i32 m0, s4, 0xe000
	s_nop 0
	global_load_lds_dwordx4 v251, s[56:57]
	s_branch .Ldiff_dma_done

; __device__ __forceinline__ unsigned cvtpk(float lo, float hi) { f32x2 v = {lo, hi}; bf16x2_t b = __builtin_convertvector(v, bf16x2_t); return __builtin_bit_cast(unsigned, b); }
; template <bool HAS_QK, bool HAS_PV> ...
;     ...
;         for (int s4 = 0; s4 < 4; ++s4) {
;             const bf16x8 a0 = KFRAG(Kt, kb0, kb1, 0, 0, s4), a1 = KFRAG(Kt, kb0, kb1, 1, 0, s4);
;             s0 = __builtin_amdgcn_mfma_f32_32x32x16_bf16(a0, qf[s4], s0, 0, 0, 0);
;             s1 = __builtin_amdgcn_mfma_f32_32x32x16_bf16(a1, qf[s4], s1, 0, 0, 0);
;         }
;     }
;     if (HAS_PV) {
; #pragma unroll
;         for (int ks = 0; ks < 2; ++ks)
; #pragma unroll
;             for (int c4 = 0; c4 < 4; ++c4) { const bf16x8 vf = vfrag(Vp, vb0, vb1, ks, c4); O[c4] = __builtin_amdgcn_mfma_f32_32x32x16_bf16(vf, P[ks], O[c4], 0, 0, 0); }
;     ...
;     if (HAS_QK) {
;         float sum0 = 0.f, sum1 = 0.f;
; #pragma unroll
;         for (int r = 0; r < 16; ++r) { s0[r] = __builtin_amdgcn_exp2f(s0[r]); s1[r] = __builtin_amdgcn_exp2f(s1[r]); sum0 += s0[r]; sum1 += s1[r]; }
; #pragma unroll
;         for (int sp = 0; sp < 2; ++sp) {
;             u32x4 w0, w1;
;             w0.x = cvtpk(s0[8 * sp + 0], s0[8 * sp + 1]); w0.y = cvtpk(s0[8 * sp + 2], s0[8 * sp + 3]); w0.z = cvtpk(s0[8 * sp + 4], s0[8 * sp + 5]); w0.w = cvtpk(s0[8 * sp + 6], s0[8 * sp + 7]);
;             w1.x = cvtpk(s1[8 * sp + 0], s1[8 * sp + 1]); w1.y = cvtpk(s1[8 * sp + 2], s1[8 * sp + 3]); w1.z = cvtpk(s1[8 * sp + 4], s1[8 * sp + 5]); w1.w = cvtpk(s1[8 * sp + 6], s1[8 * sp + 7]);
;             P[sp] = __builtin_bit_cast(bf16x8, w0); P[2 + sp] = __builtin_bit_cast(bf16x8, w1);
.Lcreg_ok_b:
	v_exp_f32_e32 v180, v129
	v_exp_f32_e32 v179, v128
	v_mfma_f32_32x32x16_bf16 v[112:127], v[220:223], v[144:147], v[194:209]
	ds_read_b64_tr_b16 v[220:221], v237 offset:16384
	ds_read_b64_tr_b16 v[222:223], v236 offset:18432
	v_exp_f32_e32 v130, v130
	v_exp_f32_e32 v131, v131
	v_exp_f32_e32 v132, v132
	v_exp_f32_e32 v133, v133
	v_mfma_f32_32x32x16_bf16 v[112:127], v[224:227], v[148:151], v[112:127]
	ds_read_b64_tr_b16 v[224:225], v237 offset:16896
	ds_read_b64_tr_b16 v[226:227], v236 offset:18944
	v_exp_f32_e32 v134, v134
	v_exp_f32_e32 v135, v135
	v_exp_f32_e32 v136, v136
	v_exp_f32_e32 v137, v137
	v_exp_f32_e32 v138, v138
	v_exp_f32_e32 v139, v139
	v_mfma_f32_32x32x16_bf16 v[112:127], v[228:231], v[152:155], v[112:127]
	ds_read_b64_tr_b16 v[228:229], v237 offset:17408
	ds_read_b64_tr_b16 v[230:231], v236 offset:19456
	v_exp_f32_e32 v140, v140
	v_exp_f32_e32 v141, v141
	v_exp_f32_e32 v142, v142
	v_exp_f32_e32 v143, v143
	s_andn2_b64 vcc, exec, s[4:5]
	v_mfma_f32_32x32x16_bf16 v[112:127], v[232:235], v[156:159], v[112:127]
	v_cvt_pk_bf16_f32 v8, v179, v180
	v_cvt_pk_bf16_f32 v9, v130, v131
	v_cvt_pk_bf16_f32 v10, v132, v133
	v_cvt_pk_bf16_f32 v11, v134, v135
	ds_read_b64_tr_b16 v[232:233], v237 offset:17920
	ds_read_b64_tr_b16 v[234:235], v236 offset:19968
	s_waitcnt lgkmcnt(6)
	v_mfma_f32_32x32x16_bf16 v[64:79], v[220:223], v[8:11], v[64:79]
	ds_read_b64_tr_b16 v[220:221], v237 offset:20480
	ds_read_b64_tr_b16 v[222:223], v236 offset:22528
	v_exp_f32_e32 v80, v80
	v_exp_f32_e32 v81, v81
	s_waitcnt lgkmcnt(6)
	v_mfma_f32_32x32x16_bf16 v[48:63], v[224:227], v[8:11], v[48:63]
	ds_read_b64_tr_b16 v[224:225], v237 offset:20992
	ds_read_b64_tr_b16 v[226:227], v236 offset:23040
	v_exp_f32_e32 v82, v82
	v_exp_f32_e32 v83, v83
	s_waitcnt lgkmcnt(6)
	v_mfma_f32_32x32x16_bf16 v[32:47], v[228:231], v[8:11], v[32:47]
	ds_read_b64_tr_b16 v[228:229], v237 offset:21504
	ds_read_b64_tr_b16 v[230:231], v236 offset:23552
	v_exp_f32_e32 v84, v84
	v_exp_f32_e32 v85, v85
	s_waitcnt lgkmcnt(6)
	v_mfma_f32_32x32x16_bf16 v[16:31], v[232:235], v[8:11], v[16:31]
	ds_read_b64_tr_b16 v[232:233], v237 offset:22016
	ds_read_b64_tr_b16 v[234:235], v236 offset:24064
	v_exp_f32_e32 v86, v86
	v_cvt_pk_bf16_f32 v8, v136, v137
	v_cvt_pk_bf16_f32 v9, v138, v139
	v_cvt_pk_bf16_f32 v10, v140, v141
	v_cvt_pk_bf16_f32 v11, v142, v143
	v_exp_f32_e32 v87, v87
	s_waitcnt lgkmcnt(6)
	v_mfma_f32_32x32x16_bf16 v[64:79], v[220:223], v[8:11], v[64:79]
	ds_read_b128 v[220:223], v248 offset:40960
	v_exp_f32_e32 v88, v88
	v_exp_f32_e32 v89, v89
	s_waitcnt lgkmcnt(5)
	v_mfma_f32_32x32x16_bf16 v[48:63], v[224:227], v[8:11], v[48:63]
	ds_read_b128 v[224:227], v249 offset:40960
	v_exp_f32_e32 v90, v90
	v_exp_f32_e32 v91, v91
	s_waitcnt lgkmcnt(4)
	v_mfma_f32_32x32x16_bf16 v[32:47], v[228:231], v[8:11], v[32:47]
	ds_read_b128 v[228:231], v248 offset:41472
	v_exp_f32_e32 v92, v92
	v_exp_f32_e32 v93, v93
	s_waitcnt lgkmcnt(3)
	v_mfma_f32_32x32x16_bf16 v[16:31], v[232:235], v[8:11], v[16:31]
	ds_read_b128 v[232:235], v249 offset:41472
	v_exp_f32_e32 v94, v94
	v_exp_f32_e32 v95, v95
	s_waitcnt lgkmcnt(3)
	v_mfma_f32_32x32x16_bf16 v[96:111], v[220:223], v[144:147], v[194:209]
	ds_read_b64_tr_b16 v[220:221], v237 offset:24576
	ds_read_b64_tr_b16 v[222:223], v236 offset:26624
	s_waitcnt lgkmcnt(4)
	v_mfma_f32_32x32x16_bf16 v[96:111], v[224:227], v[148:151], v[96:111]
	ds_read_b64_tr_b16 v[224:225], v237 offset:25088
	ds_read_b64_tr_b16 v[226:227], v236 offset:27136
	s_waitcnt lgkmcnt(5)
	v_mfma_f32_32x32x16_bf16 v[96:111], v[228:231], v[152:155], v[96:111]
	ds_read_b64_tr_b16 v[228:229], v237 offset:25600
	ds_read_b64_tr_b16 v[230:231], v236 offset:27648
	s_waitcnt lgkmcnt(6)
	v_mfma_f32_32x32x16_bf16 v[96:111], v[232:235], v[156:159], v[96:111]
	ds_read_b64_tr_b16 v[232:233], v237 offset:26112
	ds_read_b64_tr_b16 v[234:235], v236 offset:28160
	s_cbranch_vccnz .LBB0_222
	v_add_u32_e32 v14, s29, v176
	v_add_u32_e32 v2, 0xc0, v14
	v_med3_i32 v3, v2, 0, v246
	v_max_i32_e32 v2, 0xffffffe0, v2
	v_add_u32_e32 v2, 32, v2
	v_min_u32_e32 v2, 0x100, v2
	v_lshl_add_u32 v4, v2, 2, s25
	v_add_u32_e32 v2, 0xc1, v14
	v_med3_i32 v5, v2, 0, v246
	v_max_i32_e32 v2, 0xffffffe0, v2
	v_add_u32_e32 v2, 32, v2
	v_min_u32_e32 v2, 0x100, v2
	v_lshl_add_u32 v6, v2, 2, s25
	v_add_u32_e32 v2, 0xc2, v14
	v_med3_i32 v7, v2, 0, v246
	v_max_i32_e32 v2, 0xffffffe0, v2
	v_add_u32_e32 v2, 32, v2
	v_min_u32_e32 v2, 0x100, v2
	v_lshl_add_u32 v8, v2, 2, s25
	v_add_u32_e32 v2, 0xc3, v14
	v_med3_i32 v9, v2, 0, v246
	v_max_i32_e32 v2, 0xffffffe0, v2
	v_add_u32_e32 v2, 32, v2
	v_min_u32_e32 v2, 0x100, v2
	v_lshl_add_u32 v3, v3, 2, s25
	v_lshl_add_u32 v5, v5, 2, s25
	v_lshl_add_u32 v7, v7, 2, s25
	v_lshl_add_u32 v9, v9, 2, s25
	v_lshl_add_u32 v10, v2, 2, s25
	ds_read_b32 v2, v3
	ds_read_b32 v4, v4
	ds_read_b32 v3, v5
	ds_read_b32 v5, v6
	ds_read_b32 v6, v7
	ds_read_b32 v8, v8
	ds_read_b32 v7, v9
	ds_read_b32 v9, v10
	v_add_u32_e32 v10, 0xc8, v14
	v_med3_i32 v11, v10, 0, v246
	v_max_i32_e32 v10, 0xffffffe0, v10
	v_add_u32_e32 v10, 32, v10
	v_min_u32_e32 v10, 0x100, v10
	v_lshl_add_u32 v12, v10, 2, s25
	v_add_u32_e32 v10, 0xc9, v14
	v_med3_i32 v13, v10, 0, v246
	v_max_i32_e32 v10, 0xffffffe0, v10
	v_add_u32_e32 v10, 32, v10
	v_min_u32_e32 v10, 0x100, v10
	v_lshl_add_u32 v181, v10, 2, s25
	v_add_u32_e32 v10, 0xca, v14
	v_med3_i32 v182, v10, 0, v246
	v_max_i32_e32 v10, 0xffffffe0, v10
	v_add_u32_e32 v187, 0xd1, v14
	v_add_u32_e32 v10, 32, v10
	v_med3_i32 v188, v187, 0, v246
	v_max_i32_e32 v187, 0xffffffe0, v187
	v_min_u32_e32 v10, 0x100, v10
	v_add_u32_e32 v187, 32, v187
	v_lshl_add_u32 v183, v10, 2, s25
	v_add_u32_e32 v10, 0xcb, v14
; template <bool HAS_QK, bool HAS_PV> ...
;     ...
;         if (NEAR) {
; #pragma unroll
;             for (int r = 0; r < 16; ++r) { int i0 = ib0 + (r & 3) + 8 * (r >> 2), i1 = i0 + 32; i0 = min(max(i0, 0), 256); i1 = min(max(i1, 0), 256); s0[r] += tab[i0]; s1[r] += tab[i1]; }
;         }
;         const float rm = rowmax32(s0, s1);
;         need = first || __any(rm > 8.f);
;         if (need) { const float dl = first ? rm : fmaxf(rm, 0.f); mrun += dl; f = first ? 1.f : __builtin_amdgcn_exp2f(-dl);
; #pragma unroll
;             for (int r = 0; r < 16; ++r) { s0[r] -= dl; s1[r] -= dl; } }
	v_min_u32_e32 v187, 0x100, v187
	v_med3_i32 v184, v10, 0, v246
	v_max_i32_e32 v10, 0xffffffe0, v10
	v_lshl_add_u32 v190, v187, 2, s25
	v_add_u32_e32 v187, 0xd2, v14
	v_add_u32_e32 v10, 32, v10
	v_lshl_add_u32 v189, v188, 2, s25
	v_med3_i32 v188, v187, 0, v246
	v_max_i32_e32 v187, 0xffffffe0, v187
	v_lshl_add_u32 v11, v11, 2, s25
	v_lshl_add_u32 v13, v13, 2, s25
	v_lshl_add_u32 v182, v182, 2, s25
	v_min_u32_e32 v10, 0x100, v10
	v_lshl_add_u32 v185, v184, 2, s25
	v_add_u32_e32 v187, 32, v187
	v_lshl_add_u32 v186, v10, 2, s25
	ds_read_b32 v10, v11
	ds_read_b32 v12, v12
	ds_read_b32 v11, v13
	ds_read_b32 v13, v181
	ds_read_b32 v182, v182
	ds_read_b32 v184, v183
	ds_read_b32 v183, v185
	ds_read_b32 v185, v186
	v_add_u32_e32 v181, 0xd0, v14
	v_min_u32_e32 v187, 0x100, v187
	v_med3_i32 v186, v181, 0, v246
	v_max_i32_e32 v181, 0xffffffe0, v181
	v_lshl_add_u32 v192, v187, 2, s25
	v_add_u32_e32 v187, 0xd3, v14
	v_add_u32_e32 v211, 0xd9, v14
	v_add_u32_e32 v181, 32, v181
	v_lshl_add_u32 v191, v188, 2, s25
	v_med3_i32 v188, v187, 0, v246
	v_max_i32_e32 v187, 0xffffffe0, v187
	v_med3_i32 v212, v211, 0, v246
	v_min_u32_e32 v181, 0x100, v181
	v_add_u32_e32 v187, 32, v187
	v_max_i32_e32 v211, 0xffffffe0, v211
	v_lshl_add_u32 v213, v212, 2, s25
	v_add_u32_e32 v212, s29, v177
	v_lshl_add_u32 v186, v186, 2, s25
	v_lshl_add_u32 v181, v181, 2, s25
	v_min_u32_e32 v187, 0x100, v187
	v_lshl_add_u32 v193, v188, 2, s25
	v_add_u32_e32 v211, 32, v211
	v_add_u32_e32 v212, 0xdb, v212
	v_lshl_add_u32 v210, v187, 2, s25
	ds_read_b32 v186, v186
	ds_read_b32 v188, v181
	ds_read_b32 v187, v189
	ds_read_b32 v189, v190
	ds_read_b32 v190, v191
	ds_read_b32 v192, v192
	ds_read_b32 v191, v193
	ds_read_b32 v193, v210
	v_add_u32_e32 v181, 0xd8, v14
	v_min_u32_e32 v211, 0x100, v211
	v_add_u32_e32 v14, 0xda, v14
	v_med3_i32 v214, v212, 0, v246
	v_max_i32_e32 v212, 0xffffffe0, v212
	v_med3_i32 v210, v181, 0, v246
	v_max_i32_e32 v181, 0xffffffe0, v181
	v_lshl_add_u32 v218, v211, 2, s25
	v_med3_i32 v211, v14, 0, v246
	v_max_i32_e32 v14, 0xffffffe0, v14
	v_add_u32_e32 v212, 32, v212
	v_add_u32_e32 v181, 32, v181
	v_add_u32_e32 v14, 32, v14
	v_min_u32_e32 v212, 0x100, v212
	v_min_u32_e32 v181, 0x100, v181
	v_lshl_add_u32 v210, v210, 2, s25
	v_min_u32_e32 v14, 0x100, v14
	v_lshl_add_u32 v211, v211, 2, s25
	v_lshl_add_u32 v215, v214, 2, s25
	v_lshl_add_u32 v216, v212, 2, s25
	v_lshl_add_u32 v181, v181, 2, s25
	v_lshl_add_u32 v14, v14, 2, s25
	ds_read_b32 v210, v210
	ds_read_b32 v212, v181
	ds_read_b32 v214, v211
	ds_read_b32 v215, v215
	ds_read_b32 v211, v213
	ds_read_b32 v217, v216
	ds_read_b32 v216, v14
	ds_read_b32 v213, v218
	s_waitcnt lgkmcnt(0)
	v_pk_add_f32 v[126:127], v[126:127], v[214:215]
	v_pk_add_f32 v[124:125], v[124:125], v[210:211]
	v_pk_add_f32 v[122:123], v[122:123], v[190:191]
	v_pk_add_f32 v[120:121], v[120:121], v[186:187]
	v_pk_add_f32 v[118:119], v[118:119], v[182:183]
	v_pk_add_f32 v[116:117], v[116:117], v[10:11]
	v_pk_add_f32 v[114:115], v[114:115], v[6:7]
	v_pk_add_f32 v[112:113], v[112:113], v[2:3]
	v_pk_add_f32 v[110:111], v[110:111], v[216:217]
	v_pk_add_f32 v[108:109], v[108:109], v[212:213]
	v_pk_add_f32 v[106:107], v[106:107], v[192:193]
	v_pk_add_f32 v[104:105], v[104:105], v[188:189]
	v_pk_add_f32 v[102:103], v[102:103], v[184:185]
	v_pk_add_f32 v[100:101], v[100:101], v[12:13]
	v_pk_add_f32 v[98:99], v[98:99], v[8:9]
	v_pk_add_f32 v[96:97], v[96:97], v[4:5]
.LBB0_222:
	v_max_f32_e32 v2, v112, v113
	v_max_f32_e32 v3, v114, v115
	v_max3_f32 v2, v2, v116, v117
	v_max3_f32 v3, v3, v118, v119
	v_max3_f32 v2, v2, v120, v121
	v_max3_f32 v3, v3, v122, v123
	v_max3_f32 v2, v2, v124, v125
	v_max3_f32 v3, v3, v126, v127
	s_nop 3
	v_max3_f32 v2, v2, v96, v97
	v_max3_f32 v3, v3, v98, v99
	v_max3_f32 v2, v2, v100, v101
	v_max3_f32 v3, v3, v102, v103
	v_max3_f32 v2, v2, v104, v105
	v_max3_f32 v3, v3, v106, v107
	v_max3_f32 v2, v2, v108, v109
	v_max3_f32 v3, v3, v110, v111
	v_max_f32_e32 v2, v2, v3
	v_cmp_lt_f32_e32 vcc, s86, v2
	s_cmp_lg_u64 vcc, 0
	s_cselect_b64 s[4:5], -1, 0
	s_cbranch_vccz .LBB0_224
	v_mov_b32_e32 v3, v2
	s_nop 1
	v_permlane32_swap_b32_e32 v2, v3
	v_max_f32_e32 v2, v2, v3
	v_max_f32_e32 v2, v2, v2
	v_max_f32_e32 v2, 0, v2
	v_exp_f32_e64 v14, -v2
	v_add_f32_e32 v15, v15, v2
	v_pk_add_f32 v[112:113], v[112:113], v[2:3] op_sel_hi:[1,0] neg_lo:[0,1] neg_hi:[0,1]
	v_pk_add_f32 v[96:97], v[96:97], v[2:3] op_sel_hi:[1,0] neg_lo:[0,1] neg_hi:[0,1]
	v_pk_add_f32 v[114:115], v[114:115], v[2:3] op_sel_hi:[1,0] neg_lo:[0,1] neg_hi:[0,1]
	v_pk_add_f32 v[98:99], v[98:99], v[2:3] op_sel_hi:[1,0] neg_lo:[0,1] neg_hi:[0,1]
	v_pk_add_f32 v[116:117], v[116:117], v[2:3] op_sel_hi:[1,0] neg_lo:[0,1] neg_hi:[0,1]
	v_pk_add_f32 v[100:101], v[100:101], v[2:3] op_sel_hi:[1,0] neg_lo:[0,1] neg_hi:[0,1]
	v_pk_add_f32 v[118:119], v[118:119], v[2:3] op_sel_hi:[1,0] neg_lo:[0,1] neg_hi:[0,1]
	v_pk_add_f32 v[102:103], v[102:103], v[2:3] op_sel_hi:[1,0] neg_lo:[0,1] neg_hi:[0,1]
	v_pk_add_f32 v[120:121], v[120:121], v[2:3] op_sel_hi:[1,0] neg_lo:[0,1] neg_hi:[0,1]
	v_pk_add_f32 v[104:105], v[104:105], v[2:3] op_sel_hi:[1,0] neg_lo:[0,1] neg_hi:[0,1]
	v_pk_add_f32 v[122:123], v[122:123], v[2:3] op_sel_hi:[1,0] neg_lo:[0,1] neg_hi:[0,1]
	v_pk_add_f32 v[106:107], v[106:107], v[2:3] op_sel_hi:[1,0] neg_lo:[0,1] neg_hi:[0,1]
	v_pk_add_f32 v[124:125], v[124:125], v[2:3] op_sel_hi:[1,0] neg_lo:[0,1] neg_hi:[0,1]
	v_pk_add_f32 v[108:109], v[108:109], v[2:3] op_sel_hi:[1,0] neg_lo:[0,1] neg_hi:[0,1]
	v_pk_add_f32 v[126:127], v[126:127], v[2:3] op_sel_hi:[1,0] neg_lo:[0,1] neg_hi:[0,1]
	v_pk_add_f32 v[110:111], v[110:111], v[2:3] op_sel_hi:[1,0] neg_lo:[0,1] neg_hi:[0,1]
	s_branch .LBB0_225
